# attention loop: the peeled last tile's softmax fillers spread by cost over its PV gaps (was 5 per gap in three groups)
# speedup vs baseline: 1.0012x; 1.0012x over previous
; #define SBAR() __builtin_amdgcn_sched_barrier(0)
; template <int KS> __device__ __forceinline__ void pv_ks(f32x16* o, int vb, bf16x8 pa) {
;     const s16x4 l0 = tr_read<v_rd_off(0, KS, 0)>(vb), h0 = tr_read<v_rd_off(0, KS, 1)>(vb), l1 = tr_read<v_rd_off(1, KS, 0)>(vb), h1 = tr_read<v_rd_off(1, KS, 1)>(vb);
;     const s16x4 l2 = tr_read<v_rd_off(2, KS, 0)>(vb), h2 = tr_read<v_rd_off(2, KS, 1)>(vb), l3 = tr_read<v_rd_off(3, KS, 0)>(vb), h3 = tr_read<v_rd_off(3, KS, 1)>(vb);
;     ...
;     asm volatile("s_waitcnt lgkmcnt(6)" ::: "memory"); SBAR();
;     o[0] = __builtin_amdgcn_mfma_f32_32x32x16_bf16(pa, PK(l0, h0), o[0], 0, 0, 0);
;     asm volatile("s_waitcnt lgkmcnt(4)" ::: "memory"); SBAR();
;     o[1] = __builtin_amdgcn_mfma_f32_32x32x16_bf16(pa, PK(l1, h1), o[1], 0, 0, 0);
;     asm volatile("s_waitcnt lgkmcnt(2)" ::: "memory"); SBAR();
;     o[2] = __builtin_amdgcn_mfma_f32_32x32x16_bf16(pa, PK(l2, h2), o[2], 0, 0, 0);
;     asm volatile("s_waitcnt lgkmcnt(0)" ::: "memory"); SBAR();
;     o[3] = __builtin_amdgcn_mfma_f32_32x32x16_bf16(pa, PK(l3, h3), o[3], 0, 0, 0);
;     ...
; }
; __device__ __forceinline__ void pv_d0(f32x16* o, int vb, bf16x8 pa0, bf16x8 pa1, bf16x8 pa2, bf16x8 pa3) {
;     __builtin_amdgcn_s_setprio(1);
;     pv_ks<0>(o, vb, pa0); pv_ks<1>(o, vb, pa1); pv_ks<2>(o, vb, pa2); pv_ks<3>(o, vb, pa3);
;     __builtin_amdgcn_s_setprio(0);
; }
; __device__ __forceinline__ void exp_half(f32x16& p) {
; #pragma unroll
;     for (int r = 0; r < 16; ++r) p[r] = __builtin_amdgcn_exp2f(p[r]);
; }
; __device__ __forceinline__ void pack_p(const f32x16& p0, const f32x16& p1, float& l_reg, bf16x8& pa0, bf16x8& pa1, bf16x8& pa2, bf16x8& pa3) {
;     float ps = 0;
; #pragma unroll
;     for (int r = 0; r < 16; ++r) ps += p0[r];
; #pragma unroll
;     for (int r = 0; r < 16; ++r) ps += p1[r];
;     l_reg += ps;
;     ...
;     PK4(p0, 0, pa0); PK4(p0, 8, pa1); PK4(p1, 0, pa2); PK4(p1, 8, pa3);
;     ...
; }
; __device__ __forceinline__ void diff_unit(const DiffArgs& A, int b, int h, int qb, char* lds, int wv) {
;     ...
;         exp_half(pA1); pack_p(pA0, pA1, l_reg, pa0, pa1, pa2, pa3); SBAR();
;         pv_d0(o, vb0 + SLOT(NT - 2), pa0, pa1, pa2, pa3); exp_half(pB0);
;         exp_half(pB1); pack_p(pB0, pB1, l_reg, pa0, pa1, pa2, pa3); SBAR();
;         pv_d0(o, vb0 + SLOT(NT - 1), pa0, pa1, pa2, pa3);
.Lsym_last1:
	s_waitcnt vmcnt(0)
	s_barrier
	s_waitcnt lgkmcnt(6)
	v_mfma_f32_32x32x16_bf16 v[48:63], v[128:131], v[144:147], v[48:63]
	ds_read_b64_tr_b16 v[144:145], v252 offset:20480
	ds_read_b64_tr_b16 v[146:147], v252 offset:22528
	v_exp_f32_e32 v120, v120
	v_exp_f32_e32 v121, v121
	v_exp_f32_e32 v122, v122
	v_exp_f32_e32 v123, v123
	s_waitcnt lgkmcnt(6)
	v_mfma_f32_32x32x16_bf16 v[32:47], v[128:131], v[148:151], v[32:47]
	ds_read_b64_tr_b16 v[148:149], v252 offset:20992
	ds_read_b64_tr_b16 v[150:151], v252 offset:23040
	v_add_f32_e32 v182, v120, v182
	v_add_f32_e32 v182, v121, v182
	v_cvt_pk_bf16_f32 v132, v120, v121
	v_exp_f32_e32 v124, v124
	v_exp_f32_e32 v125, v125
	s_waitcnt lgkmcnt(6)
	v_mfma_f32_32x32x16_bf16 v[16:31], v[128:131], v[152:155], v[16:31]
	ds_read_b64_tr_b16 v[152:153], v252 offset:21504
	ds_read_b64_tr_b16 v[154:155], v252 offset:23552
	v_add_f32_e32 v182, v122, v182
	v_add_f32_e32 v182, v123, v182
	v_cvt_pk_bf16_f32 v133, v122, v123
	v_exp_f32_e32 v126, v126
	v_exp_f32_e32 v127, v127
	v_add_f32_e32 v182, v124, v182
	s_waitcnt lgkmcnt(6)
	v_mfma_f32_32x32x16_bf16 v[0:15], v[128:131], v[156:159], v[0:15]
	ds_read_b64_tr_b16 v[156:157], v252 offset:22016
	ds_read_b64_tr_b16 v[158:159], v252 offset:24064
	v_add_f32_e32 v182, v125, v182
	v_cvt_pk_bf16_f32 v134, v124, v125
	v_cvt_pk_bf16_f32 v135, v126, v127
	v_add_f32_e32 v182, v126, v182
	v_add_f32_e32 v182, v127, v182
	v_exp_f32_e32 v96, v96
	s_waitcnt lgkmcnt(6)
	v_mfma_f32_32x32x16_bf16 v[48:63], v[132:135], v[144:147], v[48:63]
	ds_read_b64_tr_b16 v[144:145], v252 offset:24576
	ds_read_b64_tr_b16 v[146:147], v252 offset:26624
	v_exp_f32_e32 v97, v97
	v_exp_f32_e32 v98, v98
	v_exp_f32_e32 v99, v99
	v_add_f32_e32 v182, v96, v182
	v_add_f32_e32 v182, v97, v182
	s_waitcnt lgkmcnt(6)
	v_mfma_f32_32x32x16_bf16 v[32:47], v[132:135], v[148:151], v[32:47]
	ds_read_b64_tr_b16 v[148:149], v252 offset:25088
	ds_read_b64_tr_b16 v[150:151], v252 offset:27136
	v_cvt_pk_bf16_f32 v136, v96, v97
	v_exp_f32_e32 v100, v100
	v_exp_f32_e32 v101, v101
	v_add_f32_e32 v182, v98, v182
	v_add_f32_e32 v182, v99, v182
	v_cvt_pk_bf16_f32 v137, v98, v99
	s_waitcnt lgkmcnt(6)
	v_mfma_f32_32x32x16_bf16 v[16:31], v[132:135], v[152:155], v[16:31]
	ds_read_b64_tr_b16 v[152:153], v252 offset:25600
	ds_read_b64_tr_b16 v[154:155], v252 offset:27648
	v_exp_f32_e32 v102, v102
	v_exp_f32_e32 v103, v103
	v_add_f32_e32 v182, v100, v182
	v_add_f32_e32 v182, v101, v182
	v_cvt_pk_bf16_f32 v138, v100, v101
	s_waitcnt lgkmcnt(6)
	v_mfma_f32_32x32x16_bf16 v[0:15], v[132:135], v[156:159], v[0:15]
	ds_read_b64_tr_b16 v[156:157], v252 offset:26112
	ds_read_b64_tr_b16 v[158:159], v252 offset:28160
	v_cvt_pk_bf16_f32 v139, v102, v103
	v_add_f32_e32 v182, v102, v182
	v_add_f32_e32 v182, v103, v182
	v_exp_f32_e32 v104, v104
	v_exp_f32_e32 v105, v105
	v_exp_f32_e32 v106, v106
	s_waitcnt lgkmcnt(6)
	v_mfma_f32_32x32x16_bf16 v[48:63], v[136:139], v[144:147], v[48:63]
	ds_read_b64_tr_b16 v[144:145], v252 offset:28672
	ds_read_b64_tr_b16 v[146:147], v252 offset:30720
	v_exp_f32_e32 v107, v107
	v_add_f32_e32 v182, v104, v182
	v_add_f32_e32 v182, v105, v182
	v_cvt_pk_bf16_f32 v140, v104, v105
	v_exp_f32_e32 v108, v108
	s_waitcnt lgkmcnt(6)
	v_mfma_f32_32x32x16_bf16 v[32:47], v[136:139], v[148:151], v[32:47]
	ds_read_b64_tr_b16 v[148:149], v252 offset:29184
	ds_read_b64_tr_b16 v[150:151], v252 offset:31232
	v_exp_f32_e32 v109, v109
	v_add_f32_e32 v182, v106, v182
	v_add_f32_e32 v182, v107, v182
	v_cvt_pk_bf16_f32 v141, v106, v107
	v_exp_f32_e32 v110, v110
	s_waitcnt lgkmcnt(6)
	v_mfma_f32_32x32x16_bf16 v[16:31], v[136:139], v[152:155], v[16:31]
	ds_read_b64_tr_b16 v[152:153], v252 offset:29696
	ds_read_b64_tr_b16 v[154:155], v252 offset:31744
	v_exp_f32_e32 v111, v111
	v_add_f32_e32 v182, v108, v182
	v_add_f32_e32 v182, v109, v182
	v_cvt_pk_bf16_f32 v142, v108, v109
	v_cvt_pk_bf16_f32 v143, v110, v111
	v_add_f32_e32 v182, v110, v182
	v_add_f32_e32 v182, v111, v182
	s_waitcnt lgkmcnt(6)
	v_mfma_f32_32x32x16_bf16 v[0:15], v[136:139], v[156:159], v[0:15]
	ds_read_b64_tr_b16 v[156:157], v252 offset:30208
	ds_read_b64_tr_b16 v[158:159], v252 offset:32256
	s_waitcnt lgkmcnt(6)
	v_mfma_f32_32x32x16_bf16 v[48:63], v[140:143], v[144:147], v[48:63]
	s_waitcnt lgkmcnt(4)
	v_mfma_f32_32x32x16_bf16 v[32:47], v[140:143], v[148:151], v[32:47]
	s_waitcnt lgkmcnt(2)
	v_mfma_f32_32x32x16_bf16 v[16:31], v[140:143], v[152:155], v[16:31]
	s_waitcnt lgkmcnt(0)
	v_mfma_f32_32x32x16_bf16 v[0:15], v[140:143], v[156:159], v[0:15]
	s_branch .Lsym_done
; #define SBAR() __builtin_amdgcn_sched_barrier(0)
; template <int KS> __device__ __forceinline__ void pv_ks(f32x16* o, int vb, bf16x8 pa) {
;     const s16x4 l0 = tr_read<v_rd_off(0, KS, 0)>(vb), h0 = tr_read<v_rd_off(0, KS, 1)>(vb), l1 = tr_read<v_rd_off(1, KS, 0)>(vb), h1 = tr_read<v_rd_off(1, KS, 1)>(vb);
;     const s16x4 l2 = tr_read<v_rd_off(2, KS, 0)>(vb), h2 = tr_read<v_rd_off(2, KS, 1)>(vb), l3 = tr_read<v_rd_off(3, KS, 0)>(vb), h3 = tr_read<v_rd_off(3, KS, 1)>(vb);
;     ...
;     asm volatile("s_waitcnt lgkmcnt(6)" ::: "memory"); SBAR();
;     o[0] = __builtin_amdgcn_mfma_f32_32x32x16_bf16(pa, PK(l0, h0), o[0], 0, 0, 0);
;     asm volatile("s_waitcnt lgkmcnt(4)" ::: "memory"); SBAR();
;     o[1] = __builtin_amdgcn_mfma_f32_32x32x16_bf16(pa, PK(l1, h1), o[1], 0, 0, 0);
;     asm volatile("s_waitcnt lgkmcnt(2)" ::: "memory"); SBAR();
;     o[2] = __builtin_amdgcn_mfma_f32_32x32x16_bf16(pa, PK(l2, h2), o[2], 0, 0, 0);
;     asm volatile("s_waitcnt lgkmcnt(0)" ::: "memory"); SBAR();
;     o[3] = __builtin_amdgcn_mfma_f32_32x32x16_bf16(pa, PK(l3, h3), o[3], 0, 0, 0);
;     ...
; }
; __device__ __forceinline__ void pv_d0(f32x16* o, int vb, bf16x8 pa0, bf16x8 pa1, bf16x8 pa2, bf16x8 pa3) {
;     __builtin_amdgcn_s_setprio(1);
;     pv_ks<0>(o, vb, pa0); pv_ks<1>(o, vb, pa1); pv_ks<2>(o, vb, pa2); pv_ks<3>(o, vb, pa3);
;     __builtin_amdgcn_s_setprio(0);
; }
; __device__ __forceinline__ void exp_half(f32x16& p) {
; #pragma unroll
;     for (int r = 0; r < 16; ++r) p[r] = __builtin_amdgcn_exp2f(p[r]);
; }
; __device__ __forceinline__ void pack_p(const f32x16& p0, const f32x16& p1, float& l_reg, bf16x8& pa0, bf16x8& pa1, bf16x8& pa2, bf16x8& pa3) {
;     float ps = 0;
; #pragma unroll
;     for (int r = 0; r < 16; ++r) ps += p0[r];
; #pragma unroll
;     for (int r = 0; r < 16; ++r) ps += p1[r];
;     l_reg += ps;
;     ...
;     PK4(p0, 0, pa0); PK4(p0, 8, pa1); PK4(p1, 0, pa2); PK4(p1, 8, pa3);
;     ...
; }
; __device__ __forceinline__ void diff_unit(const DiffArgs& A, int b, int h, int qb, char* lds, int wv) {
;     ...
;         exp_half(pA1); pack_p(pA0, pA1, l_reg, pa0, pa1, pa2, pa3); SBAR();
;         pv_d0(o, vb0 + SLOT(NT - 2), pa0, pa1, pa2, pa3); exp_half(pB0);
;         exp_half(pB1); pack_p(pB0, pB1, l_reg, pa0, pa1, pa2, pa3); SBAR();
;         pv_d0(o, vb0 + SLOT(NT - 1), pa0, pa1, pa2, pa3);
.Lsym_last3:
	s_waitcnt vmcnt(0)
	s_barrier
	s_waitcnt lgkmcnt(6)
	v_mfma_f32_32x32x16_bf16 v[48:63], v[128:131], v[144:147], v[48:63]
	ds_read_b64_tr_b16 v[144:145], v252 offset:53248
	ds_read_b64_tr_b16 v[146:147], v252 offset:55296
	v_exp_f32_e32 v120, v120
	v_exp_f32_e32 v121, v121
	v_exp_f32_e32 v122, v122
	v_exp_f32_e32 v123, v123
	s_waitcnt lgkmcnt(6)
	v_mfma_f32_32x32x16_bf16 v[32:47], v[128:131], v[148:151], v[32:47]
	ds_read_b64_tr_b16 v[148:149], v252 offset:53760
	ds_read_b64_tr_b16 v[150:151], v252 offset:55808
	v_add_f32_e32 v182, v120, v182
	v_add_f32_e32 v182, v121, v182
	v_cvt_pk_bf16_f32 v132, v120, v121
	v_exp_f32_e32 v124, v124
	v_exp_f32_e32 v125, v125
	s_waitcnt lgkmcnt(6)
	v_mfma_f32_32x32x16_bf16 v[16:31], v[128:131], v[152:155], v[16:31]
	ds_read_b64_tr_b16 v[152:153], v252 offset:54272
	ds_read_b64_tr_b16 v[154:155], v252 offset:56320
	v_add_f32_e32 v182, v122, v182
	v_add_f32_e32 v182, v123, v182
	v_cvt_pk_bf16_f32 v133, v122, v123
	v_exp_f32_e32 v126, v126
	v_exp_f32_e32 v127, v127
	v_add_f32_e32 v182, v124, v182
	s_waitcnt lgkmcnt(6)
	v_mfma_f32_32x32x16_bf16 v[0:15], v[128:131], v[156:159], v[0:15]
	ds_read_b64_tr_b16 v[156:157], v252 offset:54784
	ds_read_b64_tr_b16 v[158:159], v252 offset:56832
	v_add_f32_e32 v182, v125, v182
	v_cvt_pk_bf16_f32 v134, v124, v125
	v_cvt_pk_bf16_f32 v135, v126, v127
	v_add_f32_e32 v182, v126, v182
	v_add_f32_e32 v182, v127, v182
	v_exp_f32_e32 v96, v96
	s_waitcnt lgkmcnt(6)
	v_mfma_f32_32x32x16_bf16 v[48:63], v[132:135], v[144:147], v[48:63]
	ds_read_b64_tr_b16 v[144:145], v252 offset:57344
	ds_read_b64_tr_b16 v[146:147], v252 offset:59392
	v_exp_f32_e32 v97, v97
	v_exp_f32_e32 v98, v98
	v_exp_f32_e32 v99, v99
	v_add_f32_e32 v182, v96, v182
	v_add_f32_e32 v182, v97, v182
	s_waitcnt lgkmcnt(6)
	v_mfma_f32_32x32x16_bf16 v[32:47], v[132:135], v[148:151], v[32:47]
	ds_read_b64_tr_b16 v[148:149], v252 offset:57856
	ds_read_b64_tr_b16 v[150:151], v252 offset:59904
	v_cvt_pk_bf16_f32 v136, v96, v97
	v_exp_f32_e32 v100, v100
	v_exp_f32_e32 v101, v101
	v_add_f32_e32 v182, v98, v182
	v_add_f32_e32 v182, v99, v182
	v_cvt_pk_bf16_f32 v137, v98, v99
	s_waitcnt lgkmcnt(6)
	v_mfma_f32_32x32x16_bf16 v[16:31], v[132:135], v[152:155], v[16:31]
	ds_read_b64_tr_b16 v[152:153], v252 offset:58368
	ds_read_b64_tr_b16 v[154:155], v252 offset:60416
	v_exp_f32_e32 v102, v102
	v_exp_f32_e32 v103, v103
	v_add_f32_e32 v182, v100, v182
	v_add_f32_e32 v182, v101, v182
	v_cvt_pk_bf16_f32 v138, v100, v101
	s_waitcnt lgkmcnt(6)
	v_mfma_f32_32x32x16_bf16 v[0:15], v[132:135], v[156:159], v[0:15]
	ds_read_b64_tr_b16 v[156:157], v252 offset:58880
	ds_read_b64_tr_b16 v[158:159], v252 offset:60928
	v_cvt_pk_bf16_f32 v139, v102, v103
	v_add_f32_e32 v182, v102, v182
	v_add_f32_e32 v182, v103, v182
	v_exp_f32_e32 v104, v104
	v_exp_f32_e32 v105, v105
	v_exp_f32_e32 v106, v106
	s_waitcnt lgkmcnt(6)
	v_mfma_f32_32x32x16_bf16 v[48:63], v[136:139], v[144:147], v[48:63]
	ds_read_b64_tr_b16 v[144:145], v252 offset:61440
	ds_read_b64_tr_b16 v[146:147], v252 offset:63488
	v_exp_f32_e32 v107, v107
	v_add_f32_e32 v182, v104, v182
	v_add_f32_e32 v182, v105, v182
	v_cvt_pk_bf16_f32 v140, v104, v105
	v_exp_f32_e32 v108, v108
	s_waitcnt lgkmcnt(6)
	v_mfma_f32_32x32x16_bf16 v[32:47], v[136:139], v[148:151], v[32:47]
	ds_read_b64_tr_b16 v[148:149], v252 offset:61952
	ds_read_b64_tr_b16 v[150:151], v252 offset:64000
	v_exp_f32_e32 v109, v109
	v_add_f32_e32 v182, v106, v182
	v_add_f32_e32 v182, v107, v182
	v_cvt_pk_bf16_f32 v141, v106, v107
	v_exp_f32_e32 v110, v110
	s_waitcnt lgkmcnt(6)
	v_mfma_f32_32x32x16_bf16 v[16:31], v[136:139], v[152:155], v[16:31]
	ds_read_b64_tr_b16 v[152:153], v252 offset:62464
	ds_read_b64_tr_b16 v[154:155], v252 offset:64512
	v_exp_f32_e32 v111, v111
	v_add_f32_e32 v182, v108, v182
	v_add_f32_e32 v182, v109, v182
	v_cvt_pk_bf16_f32 v142, v108, v109
	v_cvt_pk_bf16_f32 v143, v110, v111
	v_add_f32_e32 v182, v110, v182
	v_add_f32_e32 v182, v111, v182
	s_waitcnt lgkmcnt(6)
	v_mfma_f32_32x32x16_bf16 v[0:15], v[136:139], v[156:159], v[0:15]
	ds_read_b64_tr_b16 v[156:157], v252 offset:62976
	ds_read_b64_tr_b16 v[158:159], v252 offset:65024
	s_waitcnt lgkmcnt(6)
	v_mfma_f32_32x32x16_bf16 v[48:63], v[140:143], v[144:147], v[48:63]
	s_waitcnt lgkmcnt(4)
	v_mfma_f32_32x32x16_bf16 v[32:47], v[140:143], v[148:151], v[32:47]
	s_waitcnt lgkmcnt(2)
	v_mfma_f32_32x32x16_bf16 v[16:31], v[140:143], v[152:155], v[16:31]
	s_waitcnt lgkmcnt(0)
	v_mfma_f32_32x32x16_bf16 v[0:15], v[140:143], v[156:159], v[0:15]
